# speedup vs baseline: 1.0441x; 1.0078x over previous
.LBB0_587:
	v_cvt_pk_bf16_f32 v216, v222, v216
	v_cvt_pk_bf16_f32 v218, v64, v218
	v_cvt_pk_bf16_f32 v217, v223, v217
	v_cvt_pk_bf16_f32 v219, v65, v219
	v_cvt_pk_bf16_f32 v64, v228, v80
	v_cvt_pk_bf16_f32 v65, v229, v81
	v_cvt_pk_bf16_f32 v66, v230, v82
	v_cvt_pk_bf16_f32 v67, v231, v83
	v_cvt_pk_bf16_f32 v228, v194, v200
	v_cvt_pk_bf16_f32 v229, v195, v201
	v_cvt_pk_bf16_f32 v230, v206, v210
	v_cvt_pk_bf16_f32 v231, v207, v211
	s_waitcnt lgkmcnt(0)
	v_cvt_pk_bf16_f32 v92, v68, v86
	v_mfma_f32_32x32x16_bf16 v[32:47], v[156:159], v[228:231], v[32:47]
	v_cvt_pk_bf16_f32 v93, v69, v87
	v_cvt_pk_bf16_f32 v94, v70, v90
	v_cvt_pk_bf16_f32 v95, v71, v91
	v_cvt_pk_bf16_f32 v86, v182, v184
	v_cvt_pk_bf16_f32 v87, v183, v185
	v_cvt_pk_bf16_f32 v88, v186, v188
	v_cvt_pk_bf16_f32 v89, v187, v189
	v_mfma_f32_32x32x16_bf16 v[48:63], v[156:159], v[216:219], v[48:63]
	v_cvt_pk_bf16_f32 v68, v232, v84
	v_cvt_pk_bf16_f32 v69, v233, v85
	v_cvt_pk_bf16_f32 v70, v234, v220
	v_mfma_f32_32x32x16_bf16 v[0:15], v[152:155], v[228:231], v[0:15]
	v_cvt_pk_bf16_f32 v71, v235, v221
	s_and_b64 vcc, exec, s[10:11]
	v_mfma_f32_32x32x16_bf16 v[16:31], v[152:155], v[216:219], v[16:31]
	v_cvt_pk_bf16_f32 v152, v196, v202
	v_cvt_pk_bf16_f32 v153, v197, v203
	v_cvt_pk_bf16_f32 v154, v208, v212
	v_cvt_pk_bf16_f32 v155, v209, v213
	s_nop 1
	v_mfma_f32_32x32x16_bf16 v[32:47], v[148:151], v[152:155], v[32:47]
	s_cbranch_vccnz .Lda_pk1
	s_add_i32 s13, s12, 4
	s_and_b32 s13, s13, 3
	s_mulk_i32 s13, 0x5000
	s_add_i32 s13, s14, s13
	s_mov_b32 m0, s13
	s_nop 0
	global_load_lds_dwordx4 v[180:181], off
.Lda_pk1:
	v_mfma_f32_32x32x16_bf16 v[48:63], v[148:151], v[92:95], v[48:63]
	v_mfma_f32_32x32x16_bf16 v[0:15], v[144:147], v[152:155], v[0:15]
	s_cbranch_vccnz .Lda_pk2
	s_add_i32 m0, s13, 0x3000
	s_nop 0
	global_load_lds_dwordx4 v[178:179], off
.Lda_pk2:
	v_mfma_f32_32x32x16_bf16 v[16:31], v[144:147], v[92:95], v[16:31]
	v_mfma_f32_32x32x16_bf16 v[32:47], v[140:143], v[86:89], v[32:47]
	v_mfma_f32_32x32x16_bf16 v[48:63], v[140:143], v[64:67], v[48:63]
	v_mfma_f32_32x32x16_bf16 v[0:15], v[136:139], v[86:89], v[0:15]
	v_mfma_f32_32x32x16_bf16 v[16:31], v[136:139], v[64:67], v[16:31]
	v_cvt_pk_bf16_f32 v64, v190, v192
	v_cvt_pk_bf16_f32 v65, v191, v193
	v_cvt_pk_bf16_f32 v66, v198, v204
	v_cvt_pk_bf16_f32 v67, v199, v205
	s_nop 1
	v_mfma_f32_32x32x16_bf16 v[32:47], v[132:135], v[64:67], v[32:47]
	v_mfma_f32_32x32x16_bf16 v[48:63], v[132:135], v[68:71], v[48:63]
	v_mfma_f32_32x32x16_bf16 v[0:15], v[128:131], v[64:67], v[0:15]
	v_mfma_f32_32x32x16_bf16 v[16:31], v[128:131], v[68:71], v[16:31]
	s_cbranch_vccnz .Lda_lastwait
	s_waitcnt vmcnt(2)

.LBB0_654:
	v_cvt_pk_bf16_f32 v58, v152, v154
	v_cvt_pk_bf16_f32 v59, v153, v155
	v_cvt_pk_bf16_f32 v60, v156, v158
	v_cvt_pk_bf16_f32 v61, v157, v159
	s_waitcnt lgkmcnt(0)
	v_cvt_pk_bf16_f32 v50, v50, v52
	v_cvt_pk_bf16_f32 v51, v51, v53
	v_mfma_f32_32x32x16_bf16 v[16:31], v[140:143], v[58:61], v[16:31]
	v_cvt_pk_bf16_f32 v52, v54, v56
	v_cvt_pk_bf16_f32 v53, v55, v57
	v_cvt_pk_bf16_f32 v32, v32, v48
	v_cvt_pk_bf16_f32 v33, v33, v49
	v_cvt_pk_bf16_f32 v34, v34, v36
	v_cvt_pk_bf16_f32 v35, v35, v37
	v_cvt_pk_bf16_f32 v36, v38, v40
	v_mfma_f32_32x32x16_bf16 v[0:15], v[112:115], v[58:61], v[0:15]
	v_cvt_pk_bf16_f32 v37, v39, v41
	v_cvt_pk_bf16_f32 v38, v42, v44
	v_cvt_pk_bf16_f32 v39, v43, v45
	s_and_b64 vcc, exec, s[10:11]
	v_mfma_f32_32x32x16_bf16 v[16:31], v[136:139], v[50:53], v[16:31]
	s_cbranch_vccnz .Lgq_pk1
	s_add_i32 s12, s7, 2
	s_and_b32 s12, s12, 3
	s_mulk_i32 s12, 0x5000
	s_add_i32 s12, s5, s12
	s_mov_b32 m0, s12
	s_nop 0
	global_load_lds_dwordx4 v[148:149], off
.Lgq_pk1:
	v_mfma_f32_32x32x16_bf16 v[0:15], v[116:119], v[50:53], v[0:15]
	v_mfma_f32_32x32x16_bf16 v[16:31], v[132:135], v[32:35], v[16:31]
	s_cbranch_vccnz .Lgq_pk2
	s_add_i32 m0, s12, 0x3000
	s_nop 0
	global_load_lds_dwordx4 v[150:151], off
.Lgq_pk2:
	v_mfma_f32_32x32x16_bf16 v[0:15], v[124:127], v[32:35], v[0:15]
	v_mfma_f32_32x32x16_bf16 v[16:31], v[128:131], v[36:39], v[16:31]
	v_mfma_f32_32x32x16_bf16 v[0:15], v[120:123], v[36:39], v[0:15]
	s_cbranch_vccnz .Lgq_lastwait
	s_waitcnt vmcnt(2)

.LBB0_687:
	v_cvt_pk_bf16_f32 v58, v174, v176
	v_cvt_pk_bf16_f32 v59, v175, v177
	v_cvt_pk_bf16_f32 v60, v178, v180
	v_cvt_pk_bf16_f32 v61, v179, v181
	s_waitcnt lgkmcnt(0)
	v_cvt_pk_bf16_f32 v50, v50, v52
	v_cvt_pk_bf16_f32 v51, v51, v53
	v_mfma_f32_32x32x16_bf16 v[0:15], v[148:151], v[58:61], v[0:15]
	v_cvt_pk_bf16_f32 v52, v54, v56
	v_cvt_pk_bf16_f32 v53, v55, v57
	v_cvt_pk_bf16_f32 v32, v32, v48
	v_cvt_pk_bf16_f32 v33, v33, v49
	v_cvt_pk_bf16_f32 v34, v34, v36
	v_cvt_pk_bf16_f32 v35, v35, v37
	v_cvt_pk_bf16_f32 v36, v38, v40
	v_mfma_f32_32x32x16_bf16 v[16:31], v[120:123], v[58:61], v[16:31]
	v_cvt_pk_bf16_f32 v37, v39, v41
	v_cvt_pk_bf16_f32 v38, v42, v44
	v_cvt_pk_bf16_f32 v39, v43, v45
	s_and_b64 vcc, exec, s[14:15]
	v_mfma_f32_32x32x16_bf16 v[0:15], v[144:147], v[50:53], v[0:15]
	s_cbranch_vccnz .Lml_pk1
	s_and_b32 s16, s7, 3
	s_mulk_i32 s16, 0x5000
	s_add_i32 s16, s5, s16
	s_mov_b32 m0, s16
	s_nop 0
	global_load_lds_dwordx4 v[172:173], off
.Lml_pk1:
	v_mfma_f32_32x32x16_bf16 v[16:31], v[124:127], v[50:53], v[16:31]
	v_mfma_f32_32x32x16_bf16 v[0:15], v[140:143], v[32:35], v[0:15]
	s_cbranch_vccnz .Lml_pk2
	s_add_i32 m0, s16, 0x3000
	s_nop 0
	global_load_lds_dwordx4 v[156:157], off
	s_bitcmp1_b32 s5, 12
	s_cbranch_scc1 .Lml_pk2
	s_add_i32 m0, s16, 0x2000
	s_nop 0
	global_load_lds_dwordx4 v[158:159], off
.Lml_pk2:
	v_mfma_f32_32x32x16_bf16 v[16:31], v[132:135], v[32:35], v[16:31]
	v_mfma_f32_32x32x16_bf16 v[0:15], v[136:139], v[36:39], v[0:15]
	v_mfma_f32_32x32x16_bf16 v[16:31], v[128:131], v[36:39], v[16:31]
	s_cbranch_vccnz .Lml_lastwait
	s_and_b64 vcc, exec, s[2:3]
	s_cbranch_vccnz .Lml_w2
	s_waitcnt vmcnt(3)
